# v63 + 64-byte alignment of the three attention loop heads and the input-projection K-loop head (byte phase mod 8 unchanged)
# baseline (speedup 1.0000x reference)
.LBB0_381:
	v_lshrrev_b32_e32 v0, 2, v81
	v_exp_f32_e32 v3, v84
	v_exp_f32_e32 v7, v83
	v_exp_f32_e32 v6, v49
	v_exp_f32_e32 v11, v48
	v_exp_f32_e32 v10, v51
	v_exp_f32_e32 v96, v50
	v_exp_f32_e32 v15, v53
	v_exp_f32_e32 v97, v52
	v_exp_f32_e32 v2, v55
	v_exp_f32_e32 v5, v54
	v_exp_f32_e32 v4, v57
	v_exp_f32_e32 v9, v56
	v_exp_f32_e32 v8, v59
	v_exp_f32_e32 v12, v58
	v_exp_f32_e32 v13, v61
	v_exp_f32_e32 v14, v60
	s_min_i32 s2, s29, 26
	v_and_or_b32 v0, v0, 3, v158
	v_lshlrev_b32_e32 v62, 1, v81
	s_sub_i32 s54, s2, s5
	v_lshlrev_b32_e32 v0, 6, v0
	v_and_b32_e32 v48, 32, v62
	v_mov_b32_e32 v155, v154
	s_mov_b32 s29, 1
	s_cmp_lt_i32 s54, -5
	v_or3_b32 v0, v48, v0, v82
	s_cbranch_scc1 .LBB0_391
	v_lshl_or_b32 v48, s5, 6, v158
	v_sub_u32_e32 v48, v48, v80
	v_subrev_u32_e32 v48, s53, v48
	s_lshl_b32 s2, s30, 8
	v_subrev_u32_e32 v162, s2, v48
	v_mov_b64_e32 v[62:63], v[46:47]
	s_add_i32 s54, s54, 8
	s_mov_b32 s30, 0x8000
	s_movk_i32 s53, 0x4000
	s_mov_b32 s2, 0
	s_mov_b32 s29, 3
	v_mov_b64_e32 v[60:61], v[44:45]
	v_mov_b64_e32 v[58:59], v[42:43]
	v_mov_b64_e32 v[56:57], v[40:41]
	v_mov_b64_e32 v[54:55], v[38:39]
	v_mov_b64_e32 v[52:53], v[36:37]
	v_mov_b64_e32 v[50:51], v[34:35]
	v_mov_b64_e32 v[48:49], v[32:33]
	s_branch .LBB0_383
	.p2align	6

.LBB0_398:
	s_lshl_b64 s[6:7], s[6:7], 20
	s_and_b64 s[34:35], s[40:41], exec
	v_lshlrev_b32_e32 v0, 4, v2
	s_cselect_b32 s72, s93, 0
	v_lshl_or_b32 v126, v35, 10, v0
	s_cselect_b32 s27, s94, 0x4000
	s_cselect_b32 s29, s95, 0x8000
	s_add_i32 s30, s72, 0
	v_add_u32_e32 v0, s30, v126
	s_waitcnt vmcnt(0)
	s_waitcnt vmcnt(0) lgkmcnt(0)
	s_barrier
	ds_read_b128 v[38:41], v0
	ds_read_b128 v[42:45], v0 offset:512
	s_mov_b32 s53, s52
	s_mov_b32 s54, s52
	s_mov_b32 s55, s52
	s_mov_b32 s56, s52
	s_mov_b32 s57, s52
	s_mov_b32 s58, s52
	s_mov_b32 s59, s52
	s_mov_b32 s60, s52
	s_mov_b32 s61, s52
	s_mov_b32 s62, s52
	s_mov_b32 s63, s52
	s_mov_b32 s64, s52
	s_mov_b32 s65, s52
	s_mov_b32 s66, s52
	s_mov_b32 s67, s52
	v_mov_b64_e32 v[2:3], s[52:53]
	v_mov_b64_e32 v[4:5], s[54:55]
	v_mov_b64_e32 v[6:7], s[56:57]
	v_mov_b64_e32 v[8:9], s[58:59]
	v_mov_b64_e32 v[10:11], s[60:61]
	v_mov_b64_e32 v[12:13], s[62:63]
	v_mov_b64_e32 v[14:15], s[64:65]
	v_mov_b64_e32 v[16:17], s[66:67]
	v_lshlrev_b32_e32 v124, 2, v35
	v_ashrrev_i32_e32 v115, 31, v114
	s_waitcnt lgkmcnt(1)
	v_mfma_f32_32x32x16_bf16 v[18:33], v[38:41], v[110:113], v[2:17]
	v_mov_b32_e32 v128, 0
	s_mov_b32 s55, -1
	s_mov_b32 s56, 0xc0000
	s_waitcnt lgkmcnt(0)
	v_mfma_f32_32x32x16_bf16 v[2:17], v[42:45], v[110:113], v[2:17]
	ds_read_b128 v[38:41], v0 offset:2048
	ds_read_b128 v[42:45], v0 offset:2560
	s_waitcnt lgkmcnt(1)
	v_mfma_f32_32x32x16_bf16 v[18:33], v[38:41], v[106:109], v[18:33]
	s_waitcnt lgkmcnt(0)
	v_mfma_f32_32x32x16_bf16 v[2:17], v[42:45], v[106:109], v[2:17]
	ds_read_b128 v[38:41], v0 offset:4096
	ds_read_b128 v[42:45], v0 offset:4608
	s_waitcnt lgkmcnt(1)
	v_mfma_f32_32x32x16_bf16 v[18:33], v[38:41], v[102:105], v[18:33]
	s_waitcnt lgkmcnt(0)
	v_mfma_f32_32x32x16_bf16 v[2:17], v[42:45], v[102:105], v[2:17]
	ds_read_b128 v[38:41], v0 offset:6656
	ds_read_b128 v[42:45], v0 offset:6144
	v_lshrrev_b32_e32 v0, 2, v34
	v_and_or_b32 v0, v0, 3, v124
	v_lshlrev_b32_e32 v34, 1, v34
	v_lshlrev_b32_e32 v0, 6, v0
	v_and_b32_e32 v34, 32, v34
	v_or3_b32 v125, v34, v0, v36
	s_waitcnt lgkmcnt(1)
	v_mfma_f32_32x32x16_bf16 v[2:17], v[38:41], v[98:101], v[2:17]
	s_waitcnt lgkmcnt(0)
	v_mfma_f32_32x32x16_bf16 v[18:33], v[42:45], v[98:101], v[18:33]
	s_nop 9
	v_max_f32_e32 v0, v3, v3
	s_nop 0
	v_max_f32_e32 v34, v19, v19
	v_max_f32_e32 v0, v34, v0
	v_max3_f32 v34, v18, v2, v20
	v_max3_f32 v0, v0, v21, v5
	v_max3_f32 v34, v34, v4, v22
	v_max3_f32 v0, v0, v23, v7
	v_max3_f32 v34, v34, v6, v24
	v_max3_f32 v0, v0, v25, v9
	v_max3_f32 v34, v34, v8, v26
	v_max3_f32 v0, v0, v27, v11
	v_max3_f32 v34, v34, v10, v28
	v_max3_f32 v0, v0, v29, v13
	v_max3_f32 v34, v34, v12, v30
	v_max3_f32 v0, v0, v31, v15
	v_max3_f32 v34, v34, v14, v32
	v_max3_f32 v0, v0, v33, v17
	v_max3_f32 v0, v34, v16, v0
	v_mov_b32_e32 v34, v0
	s_nop 1
	v_permlane32_swap_b32 v0, v34
	s_nop 1
	s_nop 0
	v_max_f32_e32 v34, v34, v34
	v_max_f32_e32 v0, v0, v0
	v_max_f32_e32 v0, v0, v34
	v_sub_f32_e32 v18, v18, v0
	v_sub_f32_e32 v19, v19, v0
	v_sub_f32_e32 v20, v20, v0
	v_sub_f32_e32 v21, v21, v0
	v_sub_f32_e32 v22, v22, v0
	v_sub_f32_e32 v23, v23, v0
	v_sub_f32_e32 v24, v24, v0
	v_sub_f32_e32 v25, v25, v0
	v_sub_f32_e32 v26, v26, v0
	v_sub_f32_e32 v27, v27, v0
	v_sub_f32_e32 v28, v28, v0
	v_sub_f32_e32 v29, v29, v0
	v_sub_f32_e32 v30, v30, v0
	v_sub_f32_e32 v31, v31, v0
	v_sub_f32_e32 v32, v32, v0
	v_sub_f32_e32 v33, v33, v0
	v_sub_f32_e32 v79, v15, v0
	v_sub_f32_e32 v78, v14, v0
	v_exp_f32_e32 v129, v18
	v_exp_f32_e32 v131, v19
	v_exp_f32_e32 v132, v20
	v_exp_f32_e32 v135, v21
	v_exp_f32_e32 v136, v22
	v_exp_f32_e32 v139, v23
	v_exp_f32_e32 v140, v24
	v_exp_f32_e32 v143, v25
	v_exp_f32_e32 v130, v26
	v_exp_f32_e32 v133, v27
	v_exp_f32_e32 v134, v28
	v_exp_f32_e32 v137, v29
	v_exp_f32_e32 v138, v30
	v_exp_f32_e32 v141, v31
	v_exp_f32_e32 v142, v32
	v_exp_f32_e32 v144, v33
	v_mov_b32_e32 v14, v1
	v_mov_b32_e32 v15, v1
	v_add_f32_e32 v127, 0, v0
	v_sub_f32_e32 v81, v17, v0
	v_sub_f32_e32 v80, v16, v0
	v_sub_f32_e32 v77, v13, v0
	v_sub_f32_e32 v76, v12, v0
	v_sub_f32_e32 v75, v11, v0
	v_sub_f32_e32 v74, v10, v0
	v_sub_f32_e32 v73, v9, v0
	v_sub_f32_e32 v72, v8, v0
	v_sub_f32_e32 v71, v7, v0
	v_sub_f32_e32 v70, v6, v0
	v_sub_f32_e32 v69, v5, v0
	v_sub_f32_e32 v68, v4, v0
	v_sub_f32_e32 v67, v3, v0
	v_sub_f32_e32 v66, v2, v0
	v_mov_b32_e32 v0, v1
	v_mov_b32_e32 v2, v1
	v_mov_b32_e32 v3, v1
	v_mov_b32_e32 v4, v1
	v_mov_b32_e32 v5, v1
	v_mov_b32_e32 v6, v1
	v_mov_b32_e32 v7, v1
	v_mov_b32_e32 v8, v1
	v_mov_b32_e32 v9, v1
	v_mov_b32_e32 v10, v1
	v_mov_b32_e32 v11, v1
	v_mov_b32_e32 v12, v1
	v_mov_b32_e32 v13, v1
	v_mov_b64_e32 v[32:33], v[14:15]
	v_xor_b32_e32 v50, 0x80000000, v127
	v_mov_b64_e32 v[30:31], v[12:13]
	v_mov_b64_e32 v[28:29], v[10:11]
	v_mov_b64_e32 v[26:27], v[8:9]
	v_mov_b64_e32 v[24:25], v[6:7]
	v_mov_b64_e32 v[22:23], v[4:5]
	v_mov_b64_e32 v[20:21], v[2:3]
	v_mov_b64_e32 v[18:19], v[0:1]
	v_mov_b64_e32 v[16:17], v[14:15]
	v_mov_b64_e32 v[14:15], v[12:13]
	v_mov_b64_e32 v[12:13], v[10:11]
	v_mov_b64_e32 v[10:11], v[8:9]
	v_mov_b64_e32 v[8:9], v[6:7]
	v_mov_b64_e32 v[6:7], v[4:5]
	v_mov_b64_e32 v[4:5], v[2:3]
	v_mov_b64_e32 v[2:3], v[0:1]
	v_mov_b32_e32 v51, v50
	v_mov_b32_e32 v52, v50
	v_mov_b32_e32 v53, v50
	v_mov_b32_e32 v54, v50
	v_mov_b32_e32 v55, v50
	v_mov_b32_e32 v56, v50
	v_mov_b32_e32 v57, v50
	v_mov_b32_e32 v58, v50
	v_mov_b32_e32 v59, v50
	v_mov_b32_e32 v60, v50
	v_mov_b32_e32 v61, v50
	v_mov_b32_e32 v62, v50
	v_mov_b32_e32 v63, v50
	v_mov_b32_e32 v64, v50
	v_mov_b32_e32 v65, v50
	s_branch .LBB0_399
	.p2align	6

.LBB0_421:
	s_lshl_b64 s[6:7], s[6:7], 20
	s_and_b64 s[28:29], s[40:41], exec
	v_lshlrev_b32_e32 v0, 4, v2
	s_cselect_b32 s40, s93, 0
	v_lshl_or_b32 v134, v35, 10, v0
	s_cselect_b32 s28, s94, 0x5000
	s_cselect_b32 s29, s95, 0xa000
	s_add_i32 s34, s40, 0
	v_add_u32_e32 v0, s34, v134
	s_waitcnt vmcnt(0)
	s_waitcnt vmcnt(0) lgkmcnt(0)
	s_barrier
	ds_read_b128 v[38:41], v0
	ds_read_b128 v[42:45], v0 offset:512
	s_mov_b32 s53, s52
	s_mov_b32 s54, s52
	s_mov_b32 s55, s52
	s_mov_b32 s56, s52
	s_mov_b32 s57, s52
	s_mov_b32 s58, s52
	s_mov_b32 s59, s52
	s_mov_b32 s60, s52
	s_mov_b32 s61, s52
	s_mov_b32 s62, s52
	s_mov_b32 s63, s52
	s_mov_b32 s64, s52
	s_mov_b32 s65, s52
	s_mov_b32 s66, s52
	s_mov_b32 s67, s52
	v_mov_b64_e32 v[2:3], s[52:53]
	v_mov_b64_e32 v[4:5], s[54:55]
	v_mov_b64_e32 v[6:7], s[56:57]
	v_mov_b64_e32 v[8:9], s[58:59]
	v_mov_b64_e32 v[10:11], s[60:61]
	v_mov_b64_e32 v[12:13], s[62:63]
	v_mov_b64_e32 v[14:15], s[64:65]
	v_mov_b64_e32 v[16:17], s[66:67]
	v_lshlrev_b32_e32 v132, 2, v35
	s_cmp_lt_i32 s30, 4
	s_waitcnt lgkmcnt(1)
	v_mfma_f32_32x32x16_bf16 v[18:33], v[38:41], v[118:121], v[2:17]
	s_cselect_b64 s[38:39], -1, 0
	s_cmp_gt_i32 s30, 3
	s_cselect_b64 s[34:35], -1, 0
	v_mov_b32_e32 v136, 0
	s_mov_b32 s57, -1
	s_mov_b32 s58, 0xc0000
	s_waitcnt lgkmcnt(0)
	v_mfma_f32_32x32x16_bf16 v[2:17], v[42:45], v[118:121], v[2:17]
	ds_read_b128 v[38:41], v0 offset:2048
	ds_read_b128 v[42:45], v0 offset:2560
	s_waitcnt lgkmcnt(1)
	v_mfma_f32_32x32x16_bf16 v[18:33], v[38:41], v[114:117], v[18:33]
	s_waitcnt lgkmcnt(0)
	v_mfma_f32_32x32x16_bf16 v[2:17], v[42:45], v[114:117], v[2:17]
	ds_read_b128 v[38:41], v0 offset:4096
	ds_read_b128 v[42:45], v0 offset:4608
	s_waitcnt lgkmcnt(1)
	v_mfma_f32_32x32x16_bf16 v[18:33], v[38:41], v[110:113], v[18:33]
	s_waitcnt lgkmcnt(0)
	v_mfma_f32_32x32x16_bf16 v[2:17], v[42:45], v[110:113], v[2:17]
	ds_read_b128 v[38:41], v0 offset:6144
	ds_read_b128 v[42:45], v0 offset:6656
	s_waitcnt lgkmcnt(1)
	v_mfma_f32_32x32x16_bf16 v[18:33], v[38:41], v[106:109], v[18:33]
	s_waitcnt lgkmcnt(0)
	v_mfma_f32_32x32x16_bf16 v[2:17], v[42:45], v[106:109], v[2:17]
	ds_read_b128 v[38:41], v0 offset:8192
	ds_read_b128 v[42:45], v0 offset:8704
	s_waitcnt lgkmcnt(1)
	v_mfma_f32_32x32x16_bf16 v[18:33], v[38:41], v[102:105], v[18:33]
	s_waitcnt lgkmcnt(0)
	v_mfma_f32_32x32x16_bf16 v[2:17], v[42:45], v[102:105], v[2:17]
	ds_read_b128 v[38:41], v0 offset:10752
	ds_read_b128 v[42:45], v0 offset:10240
	v_lshrrev_b32_e32 v0, 2, v34
	v_and_or_b32 v0, v0, 3, v132
	v_lshlrev_b32_e32 v34, 1, v34
	v_lshlrev_b32_e32 v0, 6, v0
	v_and_b32_e32 v34, 32, v34
	v_or3_b32 v133, v34, v0, v36
	s_waitcnt lgkmcnt(1)
	v_mfma_f32_32x32x16_bf16 v[2:17], v[38:41], v[98:101], v[2:17]
	s_waitcnt lgkmcnt(0)
	v_mfma_f32_32x32x16_bf16 v[18:33], v[42:45], v[98:101], v[18:33]
	s_nop 9
	v_max_f32_e32 v0, v3, v3
	s_nop 0
	v_max_f32_e32 v34, v19, v19
	v_max_f32_e32 v0, v34, v0
	v_max3_f32 v34, v18, v2, v20
	v_max3_f32 v0, v0, v21, v5
	v_max3_f32 v34, v34, v4, v22
	v_max3_f32 v0, v0, v23, v7
	v_max3_f32 v34, v34, v6, v24
	v_max3_f32 v0, v0, v25, v9
	v_max3_f32 v34, v34, v8, v26
	v_max3_f32 v0, v0, v27, v11
	v_max3_f32 v34, v34, v10, v28
	v_max3_f32 v0, v0, v29, v13
	v_max3_f32 v34, v34, v12, v30
	v_max3_f32 v0, v0, v31, v15
	v_max3_f32 v34, v34, v14, v32
	v_max3_f32 v0, v0, v33, v17
	v_max3_f32 v0, v34, v16, v0
	v_mov_b32_e32 v34, v0
	s_nop 1
	v_permlane32_swap_b32 v0, v34
	s_nop 1
	s_nop 0
	v_max_f32_e32 v34, v34, v34
	v_max_f32_e32 v0, v0, v0
	v_max_f32_e32 v0, v0, v34
	v_sub_f32_e32 v18, v18, v0
	v_sub_f32_e32 v19, v19, v0
	v_sub_f32_e32 v20, v20, v0
	v_sub_f32_e32 v21, v21, v0
	v_sub_f32_e32 v22, v22, v0
	v_sub_f32_e32 v23, v23, v0
	v_sub_f32_e32 v24, v24, v0
	v_sub_f32_e32 v25, v25, v0
	v_sub_f32_e32 v26, v26, v0
	v_sub_f32_e32 v27, v27, v0
	v_sub_f32_e32 v28, v28, v0
	v_sub_f32_e32 v29, v29, v0
	v_sub_f32_e32 v30, v30, v0
	v_sub_f32_e32 v31, v31, v0
	v_sub_f32_e32 v32, v32, v0
	v_sub_f32_e32 v33, v33, v0
	v_sub_f32_e32 v79, v15, v0
	v_sub_f32_e32 v78, v14, v0
	v_exp_f32_e32 v141, v18
	v_exp_f32_e32 v146, v19
	v_exp_f32_e32 v138, v20
	v_exp_f32_e32 v142, v21
	v_exp_f32_e32 v143, v22
	v_exp_f32_e32 v147, v23
	v_exp_f32_e32 v148, v24
	v_exp_f32_e32 v151, v25
	v_exp_f32_e32 v137, v26
	v_exp_f32_e32 v139, v27
	v_exp_f32_e32 v140, v28
	v_exp_f32_e32 v144, v29
	v_exp_f32_e32 v145, v30
	v_exp_f32_e32 v149, v31
	v_exp_f32_e32 v150, v32
	v_exp_f32_e32 v152, v33
	v_mov_b32_e32 v14, v1
	v_mov_b32_e32 v15, v1
	v_add_f32_e32 v135, 0, v0
	v_sub_f32_e32 v81, v17, v0
	v_sub_f32_e32 v80, v16, v0
	v_sub_f32_e32 v77, v13, v0
	v_sub_f32_e32 v76, v12, v0
	v_sub_f32_e32 v75, v11, v0
	v_sub_f32_e32 v74, v10, v0
	v_sub_f32_e32 v73, v9, v0
	v_sub_f32_e32 v72, v8, v0
	v_sub_f32_e32 v71, v7, v0
	v_sub_f32_e32 v70, v6, v0
	v_sub_f32_e32 v69, v5, v0
	v_sub_f32_e32 v68, v4, v0
	v_sub_f32_e32 v67, v3, v0
	v_sub_f32_e32 v66, v2, v0
	v_mov_b32_e32 v0, v1
	v_mov_b32_e32 v2, v1
	v_mov_b32_e32 v3, v1
	v_mov_b32_e32 v4, v1
	v_mov_b32_e32 v5, v1
	v_mov_b32_e32 v6, v1
	v_mov_b32_e32 v7, v1
	v_mov_b32_e32 v8, v1
	v_mov_b32_e32 v9, v1
	v_mov_b32_e32 v10, v1
	v_mov_b32_e32 v11, v1
	v_mov_b32_e32 v12, v1
	v_mov_b32_e32 v13, v1
	v_mov_b64_e32 v[32:33], v[14:15]
	v_xor_b32_e32 v50, 0x80000000, v135
	v_mov_b64_e32 v[30:31], v[12:13]
	v_mov_b64_e32 v[28:29], v[10:11]
	v_mov_b64_e32 v[26:27], v[8:9]
	v_mov_b64_e32 v[24:25], v[6:7]
	v_mov_b64_e32 v[22:23], v[4:5]
	v_mov_b64_e32 v[20:21], v[2:3]
	v_mov_b64_e32 v[18:19], v[0:1]
	v_mov_b64_e32 v[16:17], v[14:15]
	v_mov_b64_e32 v[14:15], v[12:13]
	v_mov_b64_e32 v[12:13], v[10:11]
	v_mov_b64_e32 v[10:11], v[8:9]
	v_mov_b64_e32 v[8:9], v[6:7]
	v_mov_b64_e32 v[6:7], v[4:5]
	v_mov_b64_e32 v[4:5], v[2:3]
	v_mov_b64_e32 v[2:3], v[0:1]
	v_mov_b32_e32 v51, v50
	v_mov_b32_e32 v52, v50
	v_mov_b32_e32 v53, v50
	v_mov_b32_e32 v54, v50
	v_mov_b32_e32 v55, v50
	v_mov_b32_e32 v56, v50
	v_mov_b32_e32 v57, v50
	v_mov_b32_e32 v58, v50
	v_mov_b32_e32 v59, v50
	v_mov_b32_e32 v60, v50
	v_mov_b32_e32 v61, v50
	v_mov_b32_e32 v62, v50
	v_mov_b32_e32 v63, v50
	v_mov_b32_e32 v64, v50
	v_mov_b32_e32 v65, v50
	s_branch .LBB0_422
	.p2align	6

.LBB0_465:
	v_readlane_b32 s28, v237, 62
	v_readlane_b32 s29, v237, 63
	s_and_b64 s[34:35], s[6:7], s[28:29]
	s_and_b64 s[28:29], s[34:35], exec
	s_cselect_b32 s28, s58, s58
	s_ashr_i32 s29, s28, 31
	s_lshl_b64 s[28:29], s[28:29], 19
	s_add_u32 s66, s22, s28
	s_addc_u32 s67, s23, s29
	s_and_b64 s[28:29], s[34:35], exec
	v_mov_b32_e32 v129, 0
	s_cselect_b32 s81, s2, s43
	s_cselect_b32 s80, s30, s42
	s_andn2_b64 vcc, exec, s[62:63]
	v_mov_b32_e32 v128, v129
	v_mov_b32_e32 v127, v129
	v_mov_b32_e32 v126, v129
	v_mov_b32_e32 v125, v129
	v_mov_b32_e32 v124, v129
	v_mov_b32_e32 v123, v129
	v_mov_b32_e32 v122, v129
	v_mov_b32_e32 v113, v129
	v_mov_b32_e32 v112, v129
	v_mov_b32_e32 v111, v129
	v_mov_b32_e32 v110, v129
	v_mov_b32_e32 v109, v129
	v_mov_b32_e32 v108, v129
	v_mov_b32_e32 v107, v129
	v_mov_b32_e32 v106, v129
	v_mov_b32_e32 v97, v129
	v_mov_b32_e32 v96, v129
	v_mov_b32_e32 v95, v129
	v_mov_b32_e32 v94, v129
	v_mov_b32_e32 v93, v129
	v_mov_b32_e32 v92, v129
	v_mov_b32_e32 v91, v129
	v_mov_b32_e32 v90, v129
	v_mov_b32_e32 v81, v129
	v_mov_b32_e32 v80, v129
	v_mov_b32_e32 v79, v129
	v_mov_b32_e32 v78, v129
	v_mov_b32_e32 v77, v129
	v_mov_b32_e32 v76, v129
	v_mov_b32_e32 v75, v129
	v_mov_b32_e32 v74, v129
	v_mov_b32_e32 v121, v129
	v_mov_b32_e32 v120, v129
	v_mov_b32_e32 v119, v129
	v_mov_b32_e32 v118, v129
	v_mov_b32_e32 v117, v129
	v_mov_b32_e32 v116, v129
	v_mov_b32_e32 v115, v129
	v_mov_b32_e32 v114, v129
	v_mov_b32_e32 v105, v129
	v_mov_b32_e32 v104, v129
	v_mov_b32_e32 v103, v129
	v_mov_b32_e32 v102, v129
	v_mov_b32_e32 v101, v129
	v_mov_b32_e32 v100, v129
	v_mov_b32_e32 v99, v129
	v_mov_b32_e32 v98, v129
	v_mov_b32_e32 v89, v129
	v_mov_b32_e32 v88, v129
	v_mov_b32_e32 v87, v129
	v_mov_b32_e32 v86, v129
	v_mov_b32_e32 v85, v129
	v_mov_b32_e32 v84, v129
	v_mov_b32_e32 v83, v129
	v_mov_b32_e32 v82, v129
	v_mov_b32_e32 v73, v129
	v_mov_b32_e32 v72, v129
	v_mov_b32_e32 v71, v129
	v_mov_b32_e32 v70, v129
	v_mov_b32_e32 v69, v129
	v_mov_b32_e32 v68, v129
	v_mov_b32_e32 v67, v129
	v_mov_b32_e32 v66, v129
	v_mov_b32_e32 v65, v129
	v_mov_b32_e32 v64, v129
	v_mov_b32_e32 v63, v129
	v_mov_b32_e32 v62, v129
	v_mov_b32_e32 v61, v129
	v_mov_b32_e32 v60, v129
	v_mov_b32_e32 v59, v129
	v_mov_b32_e32 v58, v129
	v_mov_b32_e32 v49, v129
	v_mov_b32_e32 v48, v129
	v_mov_b32_e32 v47, v129
	v_mov_b32_e32 v46, v129
	v_mov_b32_e32 v45, v129
	v_mov_b32_e32 v44, v129
	v_mov_b32_e32 v43, v129
	v_mov_b32_e32 v42, v129
	v_mov_b32_e32 v33, v129
	v_mov_b32_e32 v32, v129
	v_mov_b32_e32 v31, v129
	v_mov_b32_e32 v30, v129
	v_mov_b32_e32 v29, v129
	v_mov_b32_e32 v28, v129
	v_mov_b32_e32 v27, v129
	v_mov_b32_e32 v26, v129
	v_mov_b32_e32 v17, v129
	v_mov_b32_e32 v16, v129
	v_mov_b32_e32 v15, v129
	v_mov_b32_e32 v14, v129
	v_mov_b32_e32 v13, v129
	v_mov_b32_e32 v12, v129
	v_mov_b32_e32 v11, v129
	v_mov_b32_e32 v10, v129
	v_mov_b32_e32 v57, v129
	v_mov_b32_e32 v56, v129
	v_mov_b32_e32 v55, v129
	v_mov_b32_e32 v54, v129
	v_mov_b32_e32 v53, v129
	v_mov_b32_e32 v52, v129
	v_mov_b32_e32 v51, v129
	v_mov_b32_e32 v50, v129
	v_mov_b32_e32 v41, v129
	v_mov_b32_e32 v40, v129
	v_mov_b32_e32 v39, v129
	v_mov_b32_e32 v38, v129
	v_mov_b32_e32 v37, v129
	v_mov_b32_e32 v36, v129
	v_mov_b32_e32 v35, v129
	v_mov_b32_e32 v34, v129
	v_mov_b32_e32 v25, v129
	v_mov_b32_e32 v24, v129
	v_mov_b32_e32 v23, v129
	v_mov_b32_e32 v22, v129
	v_mov_b32_e32 v21, v129
	v_mov_b32_e32 v20, v129
	v_mov_b32_e32 v19, v129
	v_mov_b32_e32 v18, v129
	v_mov_b32_e32 v9, v129
	v_mov_b32_e32 v8, v129
	v_mov_b32_e32 v7, v129
	v_mov_b32_e32 v6, v129
	v_mov_b32_e32 v5, v129
	v_mov_b32_e32 v4, v129
	v_mov_b32_e32 v3, v129
	v_mov_b32_e32 v2, v129
	s_cbranch_vccnz .LBB0_468
	s_and_b64 s[28:29], s[34:35], exec
	s_cselect_b32 s28, s67, s41
	s_cselect_b32 s29, s66, s40
	s_add_u32 s40, s40, 0x80
	s_addc_u32 s41, s41, 0
	s_add_u32 s44, s42, 0x100
	v_mov_b32_e32 v2, 0
	s_addc_u32 s45, s43, 0
	s_mov_b32 s42, 0
	v_mov_b32_e32 v3, v2
	v_mov_b32_e32 v4, v2
	v_mov_b32_e32 v5, v2
	v_mov_b32_e32 v6, v2
	v_mov_b32_e32 v7, v2
	v_mov_b32_e32 v8, v2
	v_mov_b32_e32 v9, v2
	v_mov_b32_e32 v18, v2
	v_mov_b32_e32 v19, v2
	v_mov_b32_e32 v20, v2
	v_mov_b32_e32 v21, v2
	v_mov_b32_e32 v22, v2
	v_mov_b32_e32 v23, v2
	v_mov_b32_e32 v24, v2
	v_mov_b32_e32 v25, v2
	v_mov_b32_e32 v34, v2
	v_mov_b32_e32 v35, v2
	v_mov_b32_e32 v36, v2
	v_mov_b32_e32 v37, v2
	v_mov_b32_e32 v38, v2
	v_mov_b32_e32 v39, v2
	v_mov_b32_e32 v40, v2
	v_mov_b32_e32 v41, v2
	v_mov_b32_e32 v50, v2
	v_mov_b32_e32 v51, v2
	v_mov_b32_e32 v52, v2
	v_mov_b32_e32 v53, v2
	v_mov_b32_e32 v54, v2
	v_mov_b32_e32 v55, v2
	v_mov_b32_e32 v56, v2
	v_mov_b32_e32 v57, v2
	v_mov_b32_e32 v10, v2
	v_mov_b32_e32 v11, v2
	v_mov_b32_e32 v12, v2
	v_mov_b32_e32 v13, v2
	v_mov_b32_e32 v14, v2
	v_mov_b32_e32 v15, v2
	v_mov_b32_e32 v16, v2
	v_mov_b32_e32 v17, v2
	v_mov_b32_e32 v26, v2
	v_mov_b32_e32 v27, v2
	v_mov_b32_e32 v28, v2
	v_mov_b32_e32 v29, v2
	v_mov_b32_e32 v30, v2
	v_mov_b32_e32 v31, v2
	v_mov_b32_e32 v32, v2
	v_mov_b32_e32 v33, v2
	v_mov_b32_e32 v42, v2
	v_mov_b32_e32 v43, v2
	v_mov_b32_e32 v44, v2
	v_mov_b32_e32 v45, v2
	v_mov_b32_e32 v46, v2
	v_mov_b32_e32 v47, v2
	v_mov_b32_e32 v48, v2
	v_mov_b32_e32 v49, v2
	v_mov_b32_e32 v58, v2
	v_mov_b32_e32 v59, v2
	v_mov_b32_e32 v60, v2
	v_mov_b32_e32 v61, v2
	v_mov_b32_e32 v62, v2
	v_mov_b32_e32 v63, v2
	v_mov_b32_e32 v64, v2
	v_mov_b32_e32 v65, v2
	v_mov_b32_e32 v66, v2
	v_mov_b32_e32 v67, v2
	v_mov_b32_e32 v68, v2
	v_mov_b32_e32 v69, v2
	v_mov_b32_e32 v70, v2
	v_mov_b32_e32 v71, v2
	v_mov_b32_e32 v72, v2
	v_mov_b32_e32 v73, v2
	v_mov_b32_e32 v82, v2
	v_mov_b32_e32 v83, v2
	v_mov_b32_e32 v84, v2
	v_mov_b32_e32 v85, v2
	v_mov_b32_e32 v86, v2
	v_mov_b32_e32 v87, v2
	v_mov_b32_e32 v88, v2
	v_mov_b32_e32 v89, v2
	v_mov_b32_e32 v98, v2
	v_mov_b32_e32 v99, v2
	v_mov_b32_e32 v100, v2
	v_mov_b32_e32 v101, v2
	v_mov_b32_e32 v102, v2
	v_mov_b32_e32 v103, v2
	v_mov_b32_e32 v104, v2
	v_mov_b32_e32 v105, v2
	v_mov_b32_e32 v114, v2
	v_mov_b32_e32 v115, v2
	v_mov_b32_e32 v116, v2
	v_mov_b32_e32 v117, v2
	v_mov_b32_e32 v118, v2
	v_mov_b32_e32 v119, v2
	v_mov_b32_e32 v120, v2
	v_mov_b32_e32 v121, v2
	v_mov_b32_e32 v74, v2
	v_mov_b32_e32 v75, v2
	v_mov_b32_e32 v76, v2
	v_mov_b32_e32 v77, v2
	v_mov_b32_e32 v78, v2
	v_mov_b32_e32 v79, v2
	v_mov_b32_e32 v80, v2
	v_mov_b32_e32 v81, v2
	v_mov_b32_e32 v90, v2
	v_mov_b32_e32 v91, v2
	v_mov_b32_e32 v92, v2
	v_mov_b32_e32 v93, v2
	v_mov_b32_e32 v94, v2
	v_mov_b32_e32 v95, v2
	v_mov_b32_e32 v96, v2
	v_mov_b32_e32 v97, v2
	v_mov_b32_e32 v106, v2
	v_mov_b32_e32 v107, v2
	v_mov_b32_e32 v108, v2
	v_mov_b32_e32 v109, v2
	v_mov_b32_e32 v110, v2
	v_mov_b32_e32 v111, v2
	v_mov_b32_e32 v112, v2
	v_mov_b32_e32 v113, v2
	v_mov_b32_e32 v122, v2
	v_mov_b32_e32 v123, v2
	v_mov_b32_e32 v124, v2
	v_mov_b32_e32 v125, v2
	v_mov_b32_e32 v126, v2
	v_mov_b32_e32 v127, v2
	v_mov_b32_e32 v128, v2
	v_mov_b32_e32 v129, v2
	.p2align	6
